# GEMM K loops: waves 0-3 run the copy with priority flips 2/1 (other half)
# speedup vs baseline: 1.0042x; 1.0042x over previous
;     __device__ bool next(int i, Unit& u) const {
;         const long L = (long)i * G + c; if (L >= nwg) return false;
;         int wgid = (int)L; { const int q = nwg / NXCD, r = nwg % NXCD, xcd = wgid % NXCD, off = wgid / NXCD; wgid = (xcd < r ? xcd * (q + 1) : r * (q + 1) + (xcd - r) * q) + off; }
;         const int nig = WGM * nN, gid = wgid / nig, fm = gid * WGM, gsz = (nM - fm) < WGM ? (nM - fm) : WGM;
;         u.pm = fm + ((wgid % nig) % gsz); u.pn = (wgid % nig) / gsz; return true;
; template <class Epi>
; __device__ __forceinline__ void gemm_phase(LAS unsigned char* lds, const Gemm g, const StaticOrder& S, const Epi& E) {
;     ...
;         const bool has_next = S.next(ui + 1, nxt);
;         const char* nA = has_next ? (const char*)g.A + (size_t)nxt.pm * tstepA : cA; const char* nB = has_next ? (const char*)g.Bt + (size_t)nxt.pn * tstepB : cB;
.LBB0_202:
	v_readfirstlane_b32 s98, v152
	s_nop 3
	s_cmp_lt_u32 s98, 0x100
	s_cbranch_scc1 .Lkp0_head
	s_add_i32 s35, s35, 1
	s_mul_i32 s0, s35, s38
	s_mul_hi_u32 s1, s35, s92
	s_add_i32 s1, s1, s0
	s_mul_i32 s0, s35, s92
	s_add_u32 s14, s0, s93
	s_addc_u32 s15, s1, s28
	v_cmp_gt_i64_e64 s[0:1], s[14:15], v[144:145]
	s_and_b64 vcc, exec, s[0:1]
	s_cbranch_vccnz .LBB0_204
	s_lshr_b32 s10, s14, 3
	s_mov_b32 s13, 0
	s_sub_u32 s11, s10, 0xa8
	s_cmp_ge_u32 s10, 0xa8
	s_cselect_b32 s10, s11, s10
	s_addc_u32 s13, s13, 0
	s_sub_u32 s11, s10, 0xa8
	s_cmp_ge_u32 s10, 0xa8
	s_cselect_b32 s10, s11, s10
	s_addc_u32 s13, s13, 0
	s_sub_u32 s11, s10, 0xa8
	s_cmp_ge_u32 s10, 0xa8
	s_cselect_b32 s10, s11, s10
	s_addc_u32 s13, s13, 0
	s_and_b32 s12, s14, 7
	s_lshl_b32 s12, s12, 2
	s_add_i32 s12, s12, s13
	s_lshl_b32 s12, s12, 3
	s_and_b32 s13, s10, 7
	s_add_i32 s12, s12, s13
	s_lshr_b32 s10, s10, 3

;     __device__ bool next(int i, Unit& u) const {
;         const long L = (long)i * G + c; if (L >= nwg) return false;
;         int wgid = (int)L; { const int q = nwg / NXCD, r = nwg % NXCD, xcd = wgid % NXCD, off = wgid / NXCD; wgid = (xcd < r ? xcd * (q + 1) : r * (q + 1) + (xcd - r) * q) + off; }
;         const int nig = WGM * nN, gid = wgid / nig, fm = gid * WGM, gsz = (nM - fm) < WGM ? (nM - fm) : WGM;
;         u.pm = fm + ((wgid % nig) % gsz); u.pn = (wgid % nig) / gsz; return true;
; template <class Epi>
; __device__ __forceinline__ void gemm_phase(LAS unsigned char* lds, const Gemm g, const StaticOrder& S, const Epi& E) {
;     ...
;         const bool has_next = S.next(ui + 1, nxt);
;         const char* nA = has_next ? (const char*)g.A + (size_t)nxt.pm * tstepA : cA; const char* nB = has_next ? (const char*)g.Bt + (size_t)nxt.pn * tstepB : cB;
.LBB0_675:
	v_readfirstlane_b32 s98, v152
	s_nop 3
	s_cmp_lt_u32 s98, 0x100
	s_cbranch_scc1 .Lkp1_head
	s_add_i32 s33, s33, 1
	s_mul_i32 s2, s33, s40
	s_mul_hi_u32 s3, s33, s92
	s_add_i32 s3, s3, s2
	s_mul_i32 s2, s33, s92
	s_add_u32 s18, s2, s93
	s_addc_u32 s19, s3, s41
	v_cmp_gt_i64_e64 s[2:3], s[18:19], v[168:169]
	v_cmp_lt_i64_e64 s[4:5], s[18:19], v[166:167]
	s_and_b64 vcc, exec, s[2:3]
	s_cbranch_vccnz .LBB0_681
	s_ashr_i32 s16, s18, 31
	s_lshr_b32 s16, s16, 29
	s_add_i32 s19, s18, s16
	s_and_b32 s16, s19, -8
	s_sub_i32 s18, s18, s16
	s_cmp_gt_i32 s18, -1
	s_mov_b64 s[16:17], -1
	s_cbranch_scc0 .LBB0_678
	s_lshl_b32 s20, s18, 7
	s_mov_b64 s[16:17], 0

;     __device__ bool next(int i, Unit& u) const {
;         const long L = (long)i * G + c; if (L >= nwg) return false;
;         int wgid = (int)L; { const int q = nwg / NXCD, r = nwg % NXCD, xcd = wgid % NXCD, off = wgid / NXCD; wgid = (xcd < r ? xcd * (q + 1) : r * (q + 1) + (xcd - r) * q) + off; }
;         const int nig = WGM * nN, gid = wgid / nig, fm = gid * WGM, gsz = (nM - fm) < WGM ? (nM - fm) : WGM;
;         u.pm = fm + ((wgid % nig) % gsz); u.pn = (wgid % nig) / gsz; return true;
; template <class Epi>
; __device__ __forceinline__ void gemm_phase(LAS unsigned char* lds, const Gemm g, const StaticOrder& S, const Epi& E) {
;     ...
;         const bool has_next = S.next(ui + 1, nxt);
;         const char* nA = has_next ? (const char*)g.A + (size_t)nxt.pm * tstepA : cA; const char* nB = has_next ? (const char*)g.Bt + (size_t)nxt.pn * tstepB : cB;
.LBB0_763:
	v_readfirstlane_b32 s98, v152
	s_nop 3
	s_cmp_lt_u32 s98, 0x100
	s_cbranch_scc1 .Lkp2_head
	s_add_i32 s34, s34, 1
	s_mul_i32 s0, s34, s37
	s_mul_hi_u32 s1, s34, s92
	s_add_i32 s1, s1, s0
	s_mul_i32 s0, s34, s92
	s_add_u32 s14, s0, s93
	s_addc_u32 s15, s1, s26
	v_cmp_gt_i64_e64 s[0:1], s[14:15], v[144:145]
	s_and_b64 vcc, exec, s[0:1]
	s_cbranch_vccnz .LBB0_769
	s_lshr_b32 s10, s14, 3
	s_mov_b32 s13, 0
	s_sub_u32 s11, s10, 0x80
	s_cmp_ge_u32 s10, 0x80
	s_cselect_b32 s10, s11, s10
	s_addc_u32 s13, s13, 0
	s_sub_u32 s11, s10, 0x80
	s_cmp_ge_u32 s10, 0x80
	s_cselect_b32 s10, s11, s10
	s_addc_u32 s13, s13, 0
	s_sub_u32 s11, s10, 0x80
	s_cmp_ge_u32 s10, 0x80
	s_cselect_b32 s10, s11, s10
	s_addc_u32 s13, s13, 0
	s_and_b32 s12, s14, 7
	s_lshl_b32 s12, s12, 2
	s_add_i32 s12, s12, s13
	s_lshl_b32 s12, s12, 3
	s_and_b32 s13, s10, 7
	s_add_i32 s12, s12, s13
	s_lshr_b32 s10, s10, 3

;     __device__ bool next(int i, Unit& u) const {
;         const long L = (long)i * G + c; if (L >= nwg) return false;
;         int wgid = (int)L; { const int q = nwg / NXCD, r = nwg % NXCD, xcd = wgid % NXCD, off = wgid / NXCD; wgid = (xcd < r ? xcd * (q + 1) : r * (q + 1) + (xcd - r) * q) + off; }
;         const int nig = WGM * nN, gid = wgid / nig, fm = gid * WGM, gsz = (nM - fm) < WGM ? (nM - fm) : WGM;
;         u.pm = fm + ((wgid % nig) % gsz); u.pn = (wgid % nig) / gsz; return true;
; template <class Epi>
; __device__ __forceinline__ void gemm_phase(LAS unsigned char* lds, const Gemm g, const StaticOrder& S, const Epi& E) {
;     ...
;         const bool has_next = S.next(ui + 1, nxt);
;         const char* nA = has_next ? (const char*)g.A + (size_t)nxt.pm * tstepA : cA; const char* nB = has_next ? (const char*)g.Bt + (size_t)nxt.pn * tstepB : cB;
.LBB0_837:
	v_readfirstlane_b32 s98, v152
	s_nop 3
	s_cmp_lt_u32 s98, 0x100
	s_cbranch_scc1 .Lkp3_head
	s_add_i32 s33, s33, 1
	s_mul_i32 s2, s33, s40
	s_mul_hi_u32 s3, s33, s92
	s_add_i32 s3, s3, s2
	s_mul_i32 s2, s33, s92
	s_add_u32 s18, s2, s93
	s_addc_u32 s19, s3, s41
	v_cmp_gt_i64_e64 s[2:3], s[18:19], v[168:169]
	s_and_b64 vcc, exec, s[2:3]
	s_cbranch_vccnz .LBB0_843
	s_lshr_b32 s14, s18, 3
	s_mov_b32 s17, 0
	s_sub_u32 s15, s14, 0x20
	s_cmp_ge_u32 s14, 0x20
	s_cselect_b32 s14, s15, s14
	s_addc_u32 s17, s17, 0
	s_sub_u32 s15, s14, 0x20
	s_cmp_ge_u32 s14, 0x20
	s_cselect_b32 s14, s15, s14
	s_addc_u32 s17, s17, 0
	s_sub_u32 s15, s14, 0x20
	s_cmp_ge_u32 s14, 0x20
	s_cselect_b32 s14, s15, s14
	s_addc_u32 s17, s17, 0
	s_and_b32 s16, s18, 7
	s_lshl_b32 s16, s16, 2
	s_add_i32 s16, s16, s17
	s_lshl_b32 s16, s16, 3
	s_and_b32 s17, s14, 7
	s_add_i32 s16, s16, s17
	s_lshr_b32 s14, s14, 3

;     __device__ bool next(int i, Unit& u) const {
;         const long L = (long)i * G + c; if (L >= nwg) return false;
;         int wgid = (int)L; { const int q = nwg / NXCD, r = nwg % NXCD, xcd = wgid % NXCD, off = wgid / NXCD; wgid = (xcd < r ? xcd * (q + 1) : r * (q + 1) + (xcd - r) * q) + off; }
;         const int nig = WGM * nN, gid = wgid / nig, fm = gid * WGM, gsz = (nM - fm) < WGM ? (nM - fm) : WGM;
;         u.pm = fm + ((wgid % nig) % gsz); u.pn = (wgid % nig) / gsz; return true;
; template <class Epi>
; __device__ __forceinline__ void gemm_phase(LAS unsigned char* lds, const Gemm g, const StaticOrder& S, const Epi& E) {
;     ...
;         const bool has_next = S.next(ui + 1, nxt);
;         const char* nA = has_next ? (const char*)g.A + (size_t)nxt.pm * tstepA : cA; const char* nB = has_next ? (const char*)g.Bt + (size_t)nxt.pn * tstepB : cB;
.LBB0_919:
	v_readfirstlane_b32 s98, v152
	s_nop 3
	s_cmp_lt_u32 s98, 0x100
	s_cbranch_scc1 .Lkp4_head
	s_add_i32 s34, s34, 1
	s_mul_i32 s0, s34, s37
	s_mul_hi_u32 s1, s34, s92
	s_add_i32 s1, s1, s0
	s_mul_i32 s0, s34, s92
	s_add_u32 s14, s0, s93
	s_addc_u32 s15, s1, s28
	v_cmp_gt_i64_e64 s[0:1], s[14:15], v[144:145]
	s_and_b64 vcc, exec, s[0:1]
	s_cbranch_vccnz .LBB0_921
	s_lshr_b32 s10, s14, 3
	s_mov_b32 s13, 0
	s_sub_u32 s11, s10, 0xa0
	s_cmp_ge_u32 s10, 0xa0
	s_cselect_b32 s10, s11, s10
	s_addc_u32 s13, s13, 0
	s_sub_u32 s11, s10, 0xa0
	s_cmp_ge_u32 s10, 0xa0
	s_cselect_b32 s10, s11, s10
	s_addc_u32 s13, s13, 0
	s_sub_u32 s11, s10, 0xa0
	s_cmp_ge_u32 s10, 0xa0
	s_cselect_b32 s10, s11, s10
	s_addc_u32 s13, s13, 0
	s_and_b32 s12, s14, 7
	s_lshl_b32 s12, s12, 2
	s_add_i32 s12, s12, s13
	s_lshl_b32 s12, s12, 3
	s_and_b32 s13, s10, 7
	s_add_i32 s12, s12, s13
	s_lshr_b32 s10, s10, 3

;     __device__ bool next(int i, Unit& u) const {
;         const long L = (long)i * G + c; if (L >= nwg) return false;
;         int wgid = (int)L; { const int q = nwg / NXCD, r = nwg % NXCD, xcd = wgid % NXCD, off = wgid / NXCD; wgid = (xcd < r ? xcd * (q + 1) : r * (q + 1) + (xcd - r) * q) + off; }
;         const int nig = WGM * nN, gid = wgid / nig, fm = gid * WGM, gsz = (nM - fm) < WGM ? (nM - fm) : WGM;
;         u.pm = fm + ((wgid % nig) % gsz); u.pn = (wgid % nig) / gsz; return true;
; template <class Epi>
; __device__ __forceinline__ void gemm_phase(LAS unsigned char* lds, const Gemm g, const StaticOrder& S, const Epi& E) {
;     ...
;         const bool has_next = S.next(ui + 1, nxt);
;         const char* nA = has_next ? (const char*)g.A + (size_t)nxt.pm * tstepA : cA; const char* nB = has_next ? (const char*)g.Bt + (size_t)nxt.pn * tstepB : cB;
.LBB0_1109:
	v_readfirstlane_b32 s98, v152
	s_nop 3
	s_cmp_lt_u32 s98, 0x100
	s_cbranch_scc1 .Lkp5_head
	s_add_i32 s33, s33, 1
	s_mul_i32 s2, s33, s38
	s_mul_hi_u32 s3, s33, s92
	s_add_i32 s3, s3, s2
	s_mul_i32 s2, s33, s92
	s_add_u32 s18, s2, s93
	s_addc_u32 s19, s3, s39
	v_cmp_gt_i64_e64 s[2:3], s[18:19], v[168:169]
	v_cmp_lt_i64_e64 s[4:5], s[18:19], v[166:167]
	s_and_b64 vcc, exec, s[2:3]
	s_cbranch_vccnz .LBB0_1115
	s_ashr_i32 s16, s18, 31
	s_lshr_b32 s16, s16, 29
	s_add_i32 s19, s18, s16
	s_and_b32 s16, s19, -8
	s_sub_i32 s18, s18, s16
	s_cmp_gt_i32 s18, -1
	s_mov_b64 s[16:17], -1
	s_cbranch_scc0 .LBB0_1112
	s_lshl_b32 s20, s18, 7
	s_mov_b64 s[16:17], 0

;     __device__ bool next(int i, Unit& u) const {
;         const long L = (long)i * G + c; if (L >= nwg) return false;
;         int wgid = (int)L; { const int q = nwg / NXCD, r = nwg % NXCD, xcd = wgid % NXCD, off = wgid / NXCD; wgid = (xcd < r ? xcd * (q + 1) : r * (q + 1) + (xcd - r) * q) + off; }
;         const int nig = WGM * nN, gid = wgid / nig, fm = gid * WGM, gsz = (nM - fm) < WGM ? (nM - fm) : WGM;
;         u.pm = fm + ((wgid % nig) % gsz); u.pn = (wgid % nig) / gsz; return true;
; template <class Epi>
; __device__ __forceinline__ void gemm_phase(LAS unsigned char* lds, const Gemm g, const StaticOrder& S, const Epi& E) {
;     ...
;         const bool has_next = S.next(ui + 1, nxt);
;         const char* nA = has_next ? (const char*)g.A + (size_t)nxt.pm * tstepA : cA; const char* nB = has_next ? (const char*)g.Bt + (size_t)nxt.pn * tstepB : cB;
.LBB0_1197:
	v_readfirstlane_b32 s98, v152
	s_nop 3
	s_cmp_lt_u32 s98, 0x100
	s_cbranch_scc1 .Lkp6_head
	s_add_i32 s33, s33, 1
	s_mul_i32 s0, s33, s36
	s_mul_hi_u32 s1, s33, s92
	s_add_i32 s1, s1, s0
	s_mul_i32 s0, s33, s92
	s_add_u32 s14, s0, s93
	s_addc_u32 s15, s1, s9
	v_cmp_gt_i64_e64 s[0:1], s[14:15], v[144:145]
	s_and_b64 vcc, exec, s[0:1]
	s_cbranch_vccnz .LBB0_1203
	s_lshr_b32 s10, s14, 3
	s_mov_b32 s13, 0
	s_sub_u32 s11, s10, 0x80
	s_cmp_ge_u32 s10, 0x80
	s_cselect_b32 s10, s11, s10
	s_addc_u32 s13, s13, 0
	s_sub_u32 s11, s10, 0x80
	s_cmp_ge_u32 s10, 0x80
	s_cselect_b32 s10, s11, s10
	s_addc_u32 s13, s13, 0
	s_sub_u32 s11, s10, 0x80
	s_cmp_ge_u32 s10, 0x80
	s_cselect_b32 s10, s11, s10
	s_addc_u32 s13, s13, 0
	s_and_b32 s12, s14, 7
	s_lshl_b32 s12, s12, 2
	s_add_i32 s12, s12, s13
	s_lshl_b32 s12, s12, 3
	s_and_b32 s13, s10, 7
	s_add_i32 s12, s12, s13
	s_lshr_b32 s10, s10, 3
